# attention: static s_setprio 1 for waves 0-3 instead of 4-7 (per-half comparison of the static priority raise)
# baseline (speedup 1.0000x reference)
; #define LAS __attribute__((address_space(3)))
; __device__ __forceinline__ int otid() { int t = threadIdx.x; asm volatile("" : "+v"(t)); return t; }
; __device__ __forceinline__ void attn_unit(int bh, int qb, const bf16_t* QKV, const bf16_t* KF, const float* cstab, const float* qg, bf16_t* MIX, LAS unsigned char* lds) {
;     const int tid = otid(), lane = tid & 63, r32 = lane & 31, hi = lane >> 5, wid = __builtin_amdgcn_readfirstlane(tid >> 6);
;     const int b = bh >> 3, h = bh & 7, q0 = qb * 256, qw = q0 + 32 * wid, q = qw + r32;
.LBB0_1037:
	v_mov_b32_e32 v143, v228
	s_and_b32 s29, s27, 7
	s_xor_b32 s23, s29, 15
	v_readfirstlane_b32 s2, v143
	s_ashr_i32 s39, s2, 6
	s_cmp_lt_u32 s39, 4
	s_cbranch_scc0 .Lprio_skip_att
	s_setprio 1
